# P1 preamble: i/f gate-weight staging loads batched (16 loads, one wait) instead of 8 serialized round trips
# speedup vs baseline: 1.0037x; 1.0037x over previous
.LBB0_137:
	global_load_dwordx2 v[212:213], v167, s[6:7]
	s_mov_b64 s[6:7], s[62:63]
	global_load_dwordx4 v[0:3], v167, s[6:7] offset:24
	global_load_dwordx2 v[132:133], v167, s[6:7] offset:192
	v_mov_b32_e32 v4, v208
	s_nop 0
	v_cmp_gt_i32_e32 vcc, s53, v4
	s_and_saveexec_b64 s[6:7], vcc
	s_cbranch_execz .LBB0_149
	s_mul_i32 s96, s83, 0x3108000
	v_lshrrev_b32_e32 v134, 3, v4
	v_mov_b32_e32 v135, 0xc420
	v_mul_u32_u24_e32 v134, v134, v135
	v_and_b32_e32 v135, 7, v4
	v_lshl_add_u32 v134, v135, 2, v134
	v_add_u32_e32 v134, 0x2800, v134
	v_lshlrev_b32_e32 v136, 2, v4
	s_waitcnt vmcnt(0)
	v_readfirstlane_b32 s8, v2
	v_readfirstlane_b32 s9, v3
	s_add_u32 s8, s8, s96
	s_addc_u32 s9, s9, 0
	global_load_dword v140, v134, s[8:9]
	s_add_u32 s8, s8, 0x310800
	s_addc_u32 s9, s9, 0
	global_load_dword v141, v134, s[8:9]
	s_add_u32 s8, s8, 0x310800
	s_addc_u32 s9, s9, 0
	global_load_dword v142, v134, s[8:9]
	s_add_u32 s8, s8, 0x310800
	s_addc_u32 s9, s9, 0
	global_load_dword v143, v134, s[8:9]
	s_add_u32 s8, s8, 0x310800
	s_addc_u32 s9, s9, 0
	global_load_dword v144, v134, s[8:9]
	s_add_u32 s8, s8, 0x310800
	s_addc_u32 s9, s9, 0
	global_load_dword v145, v134, s[8:9]
	s_add_u32 s8, s8, 0x310800
	s_addc_u32 s9, s9, 0
	global_load_dword v146, v134, s[8:9]
	s_add_u32 s8, s8, 0x310800
	s_addc_u32 s9, s9, 0
	global_load_dword v147, v134, s[8:9]
	s_add_u32 s8, s8, 0x310800
	s_addc_u32 s9, s9, 0
	global_load_dword v148, v134, s[8:9]
	s_add_u32 s8, s8, 0x310800
	s_addc_u32 s9, s9, 0
	global_load_dword v149, v134, s[8:9]
	s_add_u32 s8, s8, 0x310800
	s_addc_u32 s9, s9, 0
	global_load_dword v150, v134, s[8:9]
	s_add_u32 s8, s8, 0x310800
	s_addc_u32 s9, s9, 0
	global_load_dword v151, v134, s[8:9]
	s_add_u32 s8, s8, 0x310800
	s_addc_u32 s9, s9, 0
	global_load_dword v152, v134, s[8:9]
	s_add_u32 s8, s8, 0x310800
	s_addc_u32 s9, s9, 0
	global_load_dword v153, v134, s[8:9]
	s_add_u32 s8, s8, 0x310800
	s_addc_u32 s9, s9, 0
	global_load_dword v154, v134, s[8:9]
	s_add_u32 s8, s8, 0x310800
	s_addc_u32 s9, s9, 0
	global_load_dword v155, v134, s[8:9]
	s_waitcnt vmcnt(0)
	ds_write_b32 v136, v140
	ds_write_b32 v136, v141 offset:2048
	ds_write_b32 v136, v142 offset:4096
	ds_write_b32 v136, v143 offset:6144
	ds_write_b32 v136, v144 offset:8192
	ds_write_b32 v136, v145 offset:10240
	ds_write_b32 v136, v146 offset:12288
	ds_write_b32 v136, v147 offset:14336
	ds_write_b32 v136, v148 offset:16384
	ds_write_b32 v136, v149 offset:18432
	ds_write_b32 v136, v150 offset:20480
	ds_write_b32 v136, v151 offset:22528
	ds_write_b32 v136, v152 offset:24576
	ds_write_b32 v136, v153 offset:26624
	ds_write_b32 v136, v154 offset:28672
	ds_write_b32 v136, v155 offset:30720
